# v056 with all six K-loop heads at 4 bytes past a 64-byte boundary (placement test)
# baseline (speedup 1.0000x reference)
.LBB0_133:
	s_ashr_i32 s19, s18, 31
	s_lshl_b64 s[28:29], s[18:19], 19
	v_cmp_lt_i64_e32 vcc, s[62:63], v[182:183]
	s_add_u32 s62, s27, s28
	s_addc_u32 s63, s37, s29
	s_and_b64 s[28:29], vcc, exec
	s_cselect_b32 s5, s63, s67
	s_cselect_b32 s7, s62, s66
	s_ashr_i32 s17, s16, 31
	s_lshl_b64 s[28:29], s[16:17], 19
	s_add_u32 s64, s46, s28
	s_addc_u32 s65, s47, s29
	s_and_b64 s[28:29], vcc, exec
	s_cselect_b32 s17, s65, s69
	s_cselect_b32 s19, s64, s68
	s_add_u32 s66, s66, 0x40080
	s_addc_u32 s67, s67, 0
	s_add_u32 s85, s68, 0x100
	v_mov_b64_e32 v[0:1], 0
	v_mov_b64_e32 v[2:3], 0
	v_mov_b64_e32 v[4:5], 0
	v_mov_b64_e32 v[6:7], 0
	v_mov_b64_e32 v[8:9], 0
	v_mov_b64_e32 v[10:11], 0
	v_mov_b64_e32 v[12:13], 0
	v_mov_b64_e32 v[14:15], 0
	v_mov_b64_e32 v[16:17], 0
	v_mov_b64_e32 v[18:19], 0
	v_mov_b64_e32 v[20:21], 0
	v_mov_b64_e32 v[22:23], 0
	v_mov_b64_e32 v[24:25], 0
	v_mov_b64_e32 v[26:27], 0
	v_mov_b64_e32 v[28:29], 0
	v_mov_b64_e32 v[30:31], 0
	v_mov_b64_e32 v[32:33], 0
	v_mov_b64_e32 v[34:35], 0
	v_mov_b64_e32 v[36:37], 0
	v_mov_b64_e32 v[38:39], 0
	v_mov_b64_e32 v[40:41], 0
	v_mov_b64_e32 v[42:43], 0
	v_mov_b64_e32 v[44:45], 0
	v_mov_b64_e32 v[46:47], 0
	v_mov_b64_e32 v[48:49], 0
	v_mov_b64_e32 v[50:51], 0
	v_mov_b64_e32 v[52:53], 0
	v_mov_b64_e32 v[54:55], 0
	v_mov_b64_e32 v[56:57], 0
	v_mov_b64_e32 v[58:59], 0
	v_mov_b64_e32 v[60:61], 0
	v_mov_b64_e32 v[62:63], 0
	v_mov_b64_e32 v[64:65], 0
	v_mov_b64_e32 v[66:67], 0
	v_mov_b64_e32 v[68:69], 0
	v_mov_b64_e32 v[70:71], 0
	v_mov_b64_e32 v[72:73], 0
	v_mov_b64_e32 v[74:75], 0
	v_mov_b64_e32 v[76:77], 0
	v_mov_b64_e32 v[78:79], 0
	v_mov_b64_e32 v[80:81], 0
	v_mov_b64_e32 v[82:83], 0
	v_mov_b64_e32 v[84:85], 0
	v_mov_b64_e32 v[86:87], 0
	v_mov_b64_e32 v[88:89], 0
	v_mov_b64_e32 v[90:91], 0
	v_mov_b64_e32 v[92:93], 0
	v_mov_b64_e32 v[94:95], 0
	v_mov_b64_e32 v[96:97], 0
	v_mov_b64_e32 v[98:99], 0
	v_mov_b64_e32 v[100:101], 0
	v_mov_b64_e32 v[102:103], 0
	v_mov_b64_e32 v[104:105], 0
	v_mov_b64_e32 v[106:107], 0
	v_mov_b64_e32 v[108:109], 0
	v_mov_b64_e32 v[110:111], 0
	v_mov_b64_e32 v[112:113], 0
	v_mov_b64_e32 v[114:115], 0
	v_mov_b64_e32 v[116:117], 0
	v_mov_b64_e32 v[118:119], 0
	v_mov_b64_e32 v[120:121], 0
	v_mov_b64_e32 v[122:123], 0
	v_mov_b64_e32 v[124:125], 0
	v_mov_b64_e32 v[126:127], 0
	s_addc_u32 s91, s69, 0
	s_mov_b32 vcc_lo, -2
	s_waitcnt vmcnt(0)
	.p2alignl 6, 3212836864
	s_nop 0

.LBB0_412:
	s_add_i32 s13, s67, -2
	s_add_u32 s85, s62, 0x100
	v_mov_b64_e32 v[0:1], 0
	v_mov_b64_e32 v[2:3], 0
	v_mov_b64_e32 v[4:5], 0
	v_mov_b64_e32 v[6:7], 0
	v_mov_b64_e32 v[8:9], 0
	v_mov_b64_e32 v[10:11], 0
	v_mov_b64_e32 v[12:13], 0
	v_mov_b64_e32 v[14:15], 0
	v_mov_b64_e32 v[16:17], 0
	v_mov_b64_e32 v[18:19], 0
	v_mov_b64_e32 v[20:21], 0
	v_mov_b64_e32 v[22:23], 0
	v_mov_b64_e32 v[24:25], 0
	v_mov_b64_e32 v[26:27], 0
	v_mov_b64_e32 v[28:29], 0
	v_mov_b64_e32 v[30:31], 0
	v_mov_b64_e32 v[32:33], 0
	v_mov_b64_e32 v[34:35], 0
	v_mov_b64_e32 v[36:37], 0
	v_mov_b64_e32 v[38:39], 0
	v_mov_b64_e32 v[40:41], 0
	v_mov_b64_e32 v[42:43], 0
	v_mov_b64_e32 v[44:45], 0
	v_mov_b64_e32 v[46:47], 0
	v_mov_b64_e32 v[48:49], 0
	v_mov_b64_e32 v[50:51], 0
	v_mov_b64_e32 v[52:53], 0
	v_mov_b64_e32 v[54:55], 0
	v_mov_b64_e32 v[56:57], 0
	v_mov_b64_e32 v[58:59], 0
	v_mov_b64_e32 v[60:61], 0
	v_mov_b64_e32 v[62:63], 0
	v_mov_b64_e32 v[64:65], 0
	v_mov_b64_e32 v[66:67], 0
	v_mov_b64_e32 v[68:69], 0
	v_mov_b64_e32 v[70:71], 0
	v_mov_b64_e32 v[72:73], 0
	v_mov_b64_e32 v[74:75], 0
	v_mov_b64_e32 v[76:77], 0
	v_mov_b64_e32 v[78:79], 0
	v_mov_b64_e32 v[80:81], 0
	v_mov_b64_e32 v[82:83], 0
	v_mov_b64_e32 v[84:85], 0
	v_mov_b64_e32 v[86:87], 0
	v_mov_b64_e32 v[88:89], 0
	v_mov_b64_e32 v[90:91], 0
	v_mov_b64_e32 v[92:93], 0
	v_mov_b64_e32 v[94:95], 0
	v_mov_b64_e32 v[96:97], 0
	v_mov_b64_e32 v[98:99], 0
	v_mov_b64_e32 v[100:101], 0
	v_mov_b64_e32 v[102:103], 0
	v_mov_b64_e32 v[104:105], 0
	v_mov_b64_e32 v[106:107], 0
	v_mov_b64_e32 v[108:109], 0
	v_mov_b64_e32 v[110:111], 0
	v_mov_b64_e32 v[112:113], 0
	v_mov_b64_e32 v[114:115], 0
	v_mov_b64_e32 v[116:117], 0
	v_mov_b64_e32 v[118:119], 0
	v_mov_b64_e32 v[120:121], 0
	v_mov_b64_e32 v[122:123], 0
	v_mov_b64_e32 v[124:125], 0
	v_mov_b64_e32 v[126:127], 0
	s_addc_u32 s91, s63, 0
	s_mov_b32 s62, 0
	.p2alignl 6, 3212836864
	s_nop 0

.LBB0_504:
	v_mov_b64_e32 v[0:1], 0x3c6
	s_ashr_i32 s65, s64, 31
	v_cmp_lt_i64_e32 vcc, s[8:9], v[0:1]
	s_lshl_b64 s[8:9], s[64:65], 20
	s_add_u32 s66, s27, s8
	s_addc_u32 s67, s74, s9
	s_and_b64 s[8:9], vcc, exec
	s_cselect_b32 s10, s67, s5
	s_cselect_b32 s11, s66, s4
	s_ashr_i32 s63, s62, 31
	s_lshl_b64 s[8:9], s[62:63], 20
	s_add_u32 s68, s75, s8
	s_addc_u32 s69, s76, s9
	s_and_b64 s[8:9], vcc, exec
	s_cselect_b32 s63, s69, s7
	s_cselect_b32 s65, s68, s6
	s_add_u32 s4, s4, 0x80080
	s_addc_u32 s5, s5, 0
	s_add_u32 s70, s6, 0x100
	v_mov_b64_e32 v[0:1], 0
	v_mov_b64_e32 v[2:3], 0
	v_mov_b64_e32 v[4:5], 0
	v_mov_b64_e32 v[6:7], 0
	v_mov_b64_e32 v[8:9], 0
	v_mov_b64_e32 v[10:11], 0
	v_mov_b64_e32 v[12:13], 0
	v_mov_b64_e32 v[14:15], 0
	v_mov_b64_e32 v[16:17], 0
	v_mov_b64_e32 v[18:19], 0
	v_mov_b64_e32 v[20:21], 0
	v_mov_b64_e32 v[22:23], 0
	v_mov_b64_e32 v[24:25], 0
	v_mov_b64_e32 v[26:27], 0
	v_mov_b64_e32 v[28:29], 0
	v_mov_b64_e32 v[30:31], 0
	v_mov_b64_e32 v[32:33], 0
	v_mov_b64_e32 v[34:35], 0
	v_mov_b64_e32 v[36:37], 0
	v_mov_b64_e32 v[38:39], 0
	v_mov_b64_e32 v[40:41], 0
	v_mov_b64_e32 v[42:43], 0
	v_mov_b64_e32 v[44:45], 0
	v_mov_b64_e32 v[46:47], 0
	v_mov_b64_e32 v[48:49], 0
	v_mov_b64_e32 v[50:51], 0
	v_mov_b64_e32 v[52:53], 0
	v_mov_b64_e32 v[54:55], 0
	v_mov_b64_e32 v[56:57], 0
	v_mov_b64_e32 v[58:59], 0
	v_mov_b64_e32 v[60:61], 0
	v_mov_b64_e32 v[62:63], 0
	v_mov_b64_e32 v[64:65], 0
	v_mov_b64_e32 v[66:67], 0
	v_mov_b64_e32 v[68:69], 0
	v_mov_b64_e32 v[70:71], 0
	v_mov_b64_e32 v[72:73], 0
	v_mov_b64_e32 v[74:75], 0
	v_mov_b64_e32 v[76:77], 0
	v_mov_b64_e32 v[78:79], 0
	v_mov_b64_e32 v[80:81], 0
	v_mov_b64_e32 v[82:83], 0
	v_mov_b64_e32 v[84:85], 0
	v_mov_b64_e32 v[86:87], 0
	v_mov_b64_e32 v[88:89], 0
	v_mov_b64_e32 v[90:91], 0
	v_mov_b64_e32 v[92:93], 0
	v_mov_b64_e32 v[94:95], 0
	v_mov_b64_e32 v[96:97], 0
	v_mov_b64_e32 v[98:99], 0
	v_mov_b64_e32 v[100:101], 0
	v_mov_b64_e32 v[102:103], 0
	v_mov_b64_e32 v[104:105], 0
	v_mov_b64_e32 v[106:107], 0
	v_mov_b64_e32 v[108:109], 0
	v_mov_b64_e32 v[110:111], 0
	v_mov_b64_e32 v[112:113], 0
	v_mov_b64_e32 v[114:115], 0
	v_mov_b64_e32 v[116:117], 0
	v_mov_b64_e32 v[118:119], 0
	v_mov_b64_e32 v[120:121], 0
	v_mov_b64_e32 v[122:123], 0
	v_mov_b64_e32 v[124:125], 0
	v_mov_b64_e32 v[126:127], 0
	s_addc_u32 s71, s7, 0
	s_mov_b32 s72, -2
	.p2alignl 6, 3212836864
	s_nop 0

.LBB0_1113:
	s_add_i32 s85, s76, -2
	s_add_u32 s64, s64, 0x80
	s_addc_u32 s65, s65, 0
	s_add_u32 s91, s66, 0x100
	v_mov_b64_e32 v[0:1], 0
	v_mov_b64_e32 v[2:3], 0
	v_mov_b64_e32 v[4:5], 0
	v_mov_b64_e32 v[6:7], 0
	v_mov_b64_e32 v[8:9], 0
	v_mov_b64_e32 v[10:11], 0
	v_mov_b64_e32 v[12:13], 0
	v_mov_b64_e32 v[14:15], 0
	v_mov_b64_e32 v[16:17], 0
	v_mov_b64_e32 v[18:19], 0
	v_mov_b64_e32 v[20:21], 0
	v_mov_b64_e32 v[22:23], 0
	v_mov_b64_e32 v[24:25], 0
	v_mov_b64_e32 v[26:27], 0
	v_mov_b64_e32 v[28:29], 0
	v_mov_b64_e32 v[30:31], 0
	v_mov_b64_e32 v[32:33], 0
	v_mov_b64_e32 v[34:35], 0
	v_mov_b64_e32 v[36:37], 0
	v_mov_b64_e32 v[38:39], 0
	v_mov_b64_e32 v[40:41], 0
	v_mov_b64_e32 v[42:43], 0
	v_mov_b64_e32 v[44:45], 0
	v_mov_b64_e32 v[46:47], 0
	v_mov_b64_e32 v[48:49], 0
	v_mov_b64_e32 v[50:51], 0
	v_mov_b64_e32 v[52:53], 0
	v_mov_b64_e32 v[54:55], 0
	v_mov_b64_e32 v[56:57], 0
	v_mov_b64_e32 v[58:59], 0
	v_mov_b64_e32 v[60:61], 0
	v_mov_b64_e32 v[62:63], 0
	v_mov_b64_e32 v[64:65], 0
	v_mov_b64_e32 v[66:67], 0
	v_mov_b64_e32 v[68:69], 0
	v_mov_b64_e32 v[70:71], 0
	v_mov_b64_e32 v[72:73], 0
	v_mov_b64_e32 v[74:75], 0
	v_mov_b64_e32 v[76:77], 0
	v_mov_b64_e32 v[78:79], 0
	v_mov_b64_e32 v[80:81], 0
	v_mov_b64_e32 v[82:83], 0
	v_mov_b64_e32 v[84:85], 0
	v_mov_b64_e32 v[86:87], 0
	v_mov_b64_e32 v[88:89], 0
	v_mov_b64_e32 v[90:91], 0
	v_mov_b64_e32 v[92:93], 0
	v_mov_b64_e32 v[94:95], 0
	v_mov_b64_e32 v[96:97], 0
	v_mov_b64_e32 v[98:99], 0
	v_mov_b64_e32 v[100:101], 0
	v_mov_b64_e32 v[102:103], 0
	v_mov_b64_e32 v[104:105], 0
	v_mov_b64_e32 v[106:107], 0
	v_mov_b64_e32 v[108:109], 0
	v_mov_b64_e32 v[110:111], 0
	v_mov_b64_e32 v[112:113], 0
	v_mov_b64_e32 v[114:115], 0
	v_mov_b64_e32 v[116:117], 0
	v_mov_b64_e32 v[118:119], 0
	v_mov_b64_e32 v[120:121], 0
	v_mov_b64_e32 v[122:123], 0
	v_mov_b64_e32 v[124:125], 0
	v_mov_b64_e32 v[126:127], 0
	s_addc_u32 vcc_lo, s67, 0
	s_mov_b32 s66, 0
	.p2alignl 6, 3212836864
	s_nop 0

.LBB0_1281:
	s_add_i32 s5, s79, -2
	s_add_u32 s58, s58, 0x80
	s_addc_u32 s59, s59, 0
	s_add_u32 s21, s60, 0x100
	v_mov_b64_e32 v[0:1], 0
	v_mov_b64_e32 v[2:3], 0
	v_mov_b64_e32 v[4:5], 0
	v_mov_b64_e32 v[6:7], 0
	v_mov_b64_e32 v[8:9], 0
	v_mov_b64_e32 v[10:11], 0
	v_mov_b64_e32 v[12:13], 0
	v_mov_b64_e32 v[14:15], 0
	v_mov_b64_e32 v[16:17], 0
	v_mov_b64_e32 v[18:19], 0
	v_mov_b64_e32 v[20:21], 0
	v_mov_b64_e32 v[22:23], 0
	v_mov_b64_e32 v[24:25], 0
	v_mov_b64_e32 v[26:27], 0
	v_mov_b64_e32 v[28:29], 0
	v_mov_b64_e32 v[30:31], 0
	v_mov_b64_e32 v[32:33], 0
	v_mov_b64_e32 v[34:35], 0
	v_mov_b64_e32 v[36:37], 0
	v_mov_b64_e32 v[38:39], 0
	v_mov_b64_e32 v[40:41], 0
	v_mov_b64_e32 v[42:43], 0
	v_mov_b64_e32 v[44:45], 0
	v_mov_b64_e32 v[46:47], 0
	v_mov_b64_e32 v[48:49], 0
	v_mov_b64_e32 v[50:51], 0
	v_mov_b64_e32 v[52:53], 0
	v_mov_b64_e32 v[54:55], 0
	v_mov_b64_e32 v[56:57], 0
	v_mov_b64_e32 v[58:59], 0
	v_mov_b64_e32 v[60:61], 0
	v_mov_b64_e32 v[62:63], 0
	v_mov_b64_e32 v[64:65], 0
	v_mov_b64_e32 v[66:67], 0
	v_mov_b64_e32 v[68:69], 0
	v_mov_b64_e32 v[70:71], 0
	v_mov_b64_e32 v[72:73], 0
	v_mov_b64_e32 v[74:75], 0
	v_mov_b64_e32 v[76:77], 0
	v_mov_b64_e32 v[78:79], 0
	v_mov_b64_e32 v[80:81], 0
	v_mov_b64_e32 v[82:83], 0
	v_mov_b64_e32 v[84:85], 0
	v_mov_b64_e32 v[86:87], 0
	v_mov_b64_e32 v[88:89], 0
	v_mov_b64_e32 v[90:91], 0
	v_mov_b64_e32 v[92:93], 0
	v_mov_b64_e32 v[94:95], 0
	v_mov_b64_e32 v[96:97], 0
	v_mov_b64_e32 v[98:99], 0
	v_mov_b64_e32 v[100:101], 0
	v_mov_b64_e32 v[102:103], 0
	v_mov_b64_e32 v[104:105], 0
	v_mov_b64_e32 v[106:107], 0
	v_mov_b64_e32 v[108:109], 0
	v_mov_b64_e32 v[110:111], 0
	v_mov_b64_e32 v[112:113], 0
	v_mov_b64_e32 v[114:115], 0
	v_mov_b64_e32 v[116:117], 0
	v_mov_b64_e32 v[118:119], 0
	v_mov_b64_e32 v[120:121], 0
	v_mov_b64_e32 v[122:123], 0
	v_mov_b64_e32 v[124:125], 0
	v_mov_b64_e32 v[126:127], 0
	s_addc_u32 s80, s61, 0
	s_mov_b32 s60, 0
	s_waitcnt lgkmcnt(0)
	.p2alignl 6, 3212836864
	s_nop 0

.LBB0_1435:
	s_ashr_i32 s17, s16, 31
	v_cmp_lt_i64_e32 vcc, s[18:19], v[186:187]
	s_lshl_b64 s[18:19], s[16:17], 19
	s_add_u32 s18, s47, s18
	s_addc_u32 s19, s54, s19
	s_and_b64 s[20:21], vcc, exec
	s_cselect_b32 s17, s19, s7
	s_cselect_b32 s66, s18, s6
	s_ashr_i32 s13, s12, 31
	s_lshl_b64 s[20:21], s[12:13], 19
	s_add_u32 s20, s37, s20
	s_addc_u32 s21, s46, s21
	s_and_b64 s[52:53], vcc, exec
	s_cselect_b32 s13, s21, s51
	s_cselect_b32 s67, s20, s50
	s_add_u32 s6, s6, 0x40080
	s_addc_u32 s7, s7, 0
	s_add_u32 s68, s50, 0x100
	v_mov_b64_e32 v[0:1], 0
	v_mov_b64_e32 v[2:3], 0
	v_mov_b64_e32 v[4:5], 0
	v_mov_b64_e32 v[6:7], 0
	v_mov_b64_e32 v[8:9], 0
	v_mov_b64_e32 v[10:11], 0
	v_mov_b64_e32 v[12:13], 0
	v_mov_b64_e32 v[14:15], 0
	v_mov_b64_e32 v[16:17], 0
	v_mov_b64_e32 v[18:19], 0
	v_mov_b64_e32 v[20:21], 0
	v_mov_b64_e32 v[22:23], 0
	v_mov_b64_e32 v[24:25], 0
	v_mov_b64_e32 v[26:27], 0
	v_mov_b64_e32 v[28:29], 0
	v_mov_b64_e32 v[30:31], 0
	v_mov_b64_e32 v[32:33], 0
	v_mov_b64_e32 v[34:35], 0
	v_mov_b64_e32 v[36:37], 0
	v_mov_b64_e32 v[38:39], 0
	v_mov_b64_e32 v[40:41], 0
	v_mov_b64_e32 v[42:43], 0
	v_mov_b64_e32 v[44:45], 0
	v_mov_b64_e32 v[46:47], 0
	v_mov_b64_e32 v[48:49], 0
	v_mov_b64_e32 v[50:51], 0
	v_mov_b64_e32 v[52:53], 0
	v_mov_b64_e32 v[54:55], 0
	v_mov_b64_e32 v[56:57], 0
	v_mov_b64_e32 v[58:59], 0
	v_mov_b64_e32 v[60:61], 0
	v_mov_b64_e32 v[62:63], 0
	v_mov_b64_e32 v[64:65], 0
	v_mov_b64_e32 v[66:67], 0
	v_mov_b64_e32 v[68:69], 0
	v_mov_b64_e32 v[70:71], 0
	v_mov_b64_e32 v[72:73], 0
	v_mov_b64_e32 v[74:75], 0
	v_mov_b64_e32 v[76:77], 0
	v_mov_b64_e32 v[78:79], 0
	v_mov_b64_e32 v[80:81], 0
	v_mov_b64_e32 v[82:83], 0
	v_mov_b64_e32 v[84:85], 0
	v_mov_b64_e32 v[86:87], 0
	v_mov_b64_e32 v[88:89], 0
	v_mov_b64_e32 v[90:91], 0
	v_mov_b64_e32 v[92:93], 0
	v_mov_b64_e32 v[94:95], 0
	v_mov_b64_e32 v[96:97], 0
	v_mov_b64_e32 v[98:99], 0
	v_mov_b64_e32 v[100:101], 0
	v_mov_b64_e32 v[102:103], 0
	v_mov_b64_e32 v[104:105], 0
	v_mov_b64_e32 v[106:107], 0
	v_mov_b64_e32 v[108:109], 0
	v_mov_b64_e32 v[110:111], 0
	v_mov_b64_e32 v[112:113], 0
	v_mov_b64_e32 v[114:115], 0
	v_mov_b64_e32 v[116:117], 0
	v_mov_b64_e32 v[118:119], 0
	v_mov_b64_e32 v[120:121], 0
	v_mov_b64_e32 v[122:123], 0
	v_mov_b64_e32 v[124:125], 0
	v_mov_b64_e32 v[126:127], 0
	s_addc_u32 s69, s51, 0
	s_mov_b32 s70, -2
	.p2alignl 6, 3212836864
	s_nop 0
